# P7 epilogue pk math software-pipelined: exp / +1 / rcp / mul stages of the 4 register pairs interleaved instead of grouped by op type
# speedup vs baseline: 1.0043x; 1.0043x over previous
.LBB0_959:
	s_mov_b32 s98, 0xbfb8aa3b
	s_mov_b32 s99, 0xbfb8aa3b
	v_mul_f32_e32 v153, 0xbfb8aa3b, v124
	v_exp_f32_e32 v153, v153
	v_mul_f32_e32 v154, 0xbfb8aa3b, v125
	v_exp_f32_e32 v156, v154
	v_lshl_add_u32 v146, s18, 8, v148
	v_ashrrev_i32_e32 v147, 31, v146
	v_lshlrev_b64 v[154:155], 6, v[146:147]
	v_add_f32_e32 v147, 1.0, v153
	v_rcp_f32_e32 v147, v147
	v_add_f32_e32 v153, 1.0, v156
	v_rcp_f32_e32 v153, v153
	s_lshl_b32 s11, s19, 2
	v_mul_f32_e32 v124, v124, v147
	v_mul_f32_e32 v124, v124, v116
	v_mul_f32_e32 v116, v125, v153
	v_mul_f32_e32 v125, 0xbfb8aa3b, v126
	v_exp_f32_e32 v125, v125
	v_mul_f32_e32 v147, 0xbfb8aa3b, v127
	v_exp_f32_e32 v147, v147
	v_mul_f32_e32 v153, v116, v117
	v_add_f32_e32 v116, 1.0, v125
	v_rcp_f32_e32 v116, v116
	v_add_f32_e32 v117, 1.0, v147
	v_mul_f32_e32 v125, 0xbfb8aa3b, v120
	v_rcp_f32_e32 v117, v117
	v_exp_f32_e32 v125, v125
	v_mul_f32_e32 v116, v126, v116
	v_mul_f32_e32 v118, v116, v118
	v_mul_f32_e32 v116, v127, v117
	v_add_f32_e32 v117, 1.0, v125
	v_rcp_f32_e32 v117, v117
	v_mul_f32_e32 v125, 0xbfb8aa3b, v121
	v_mul_f32_e32 v119, v116, v119
	v_exp_f32_e32 v125, v125
	v_mul_f32_e32 v116, v120, v117
	v_mul_f32_e32 v120, v116, v112
	v_mul_f32_e32 v116, 0xbfb8aa3b, v122
	v_exp_f32_e32 v116, v116
	v_mul_f32_e32 v117, 0xbfb8aa3b, v123
	v_exp_f32_e32 v117, v117
	v_add_f32_e32 v112, 1.0, v125
	v_rcp_f32_e32 v112, v112
	v_add_f32_e32 v116, 1.0, v116
	v_rcp_f32_e32 v116, v116
	v_add_f32_e32 v117, 1.0, v117
	s_or_b32 s11, s11, s44
	v_rcp_f32_e32 v117, v117
	s_mul_hi_i32 s13, s11, 0x500000
	s_mul_i32 s11, s11, 0x500000
	s_add_u32 s18, s42, s11
	v_mul_f32_e32 v112, v121, v112
	s_addc_u32 s19, s43, s13
	v_mul_f32_e32 v121, v112, v113
	v_mul_f32_e32 v112, v122, v116
	v_lshl_add_u64 v[154:155], s[18:19], 0, v[154:155]
	v_mul_f32_e32 v122, v112, v114
	v_mul_f32_e32 v112, v123, v117
	v_mul_f32_e32 v115, v112, v115
	v_lshl_add_u64 v[116:117], v[154:155], 0, v[136:137]
	v_cvt_pk_bf16_f32 v112, v124, v153
	v_cvt_pk_bf16_f32 v113, v118, v119
	v_cvt_pk_bf16_f32 v114, v120, v121
	v_cvt_pk_bf16_f32 v115, v122, v115
	global_store_dwordx4 v[116:117], v[112:115], off
	s_nop 0
	s_andn2_b64 vcc, exec, s[2:3]
	s_mov_b64 s[2:3], -1
	v_or_b32_e32 v112, 16, v146
	v_ashrrev_i32_e32 v113, 31, v112
	v_lshlrev_b64 v[112:113], 6, v[112:113]
	v_lshl_add_u64 v[112:113], s[18:19], 0, v[112:113]
	v_pk_mul_f32 v[114:115], v[108:109], s[98:99]
	v_pk_mul_f32 v[116:117], v[110:111], s[98:99]
	v_pk_mul_f32 v[118:119], v[104:105], s[98:99]
	v_pk_mul_f32 v[120:121], v[106:107], s[98:99]
	v_exp_f32_e32 v114, v114
	v_exp_f32_e32 v115, v115
	v_exp_f32_e32 v116, v116
	v_exp_f32_e32 v117, v117
	v_pk_add_f32 v[114:115], v[114:115], 1.0 op_sel_hi:[1,0]
	v_exp_f32_e32 v118, v118
	v_exp_f32_e32 v119, v119
	v_pk_add_f32 v[116:117], v[116:117], 1.0 op_sel_hi:[1,0]
	v_rcp_f32_e32 v114, v114
	v_rcp_f32_e32 v115, v115
	v_exp_f32_e32 v120, v120
	v_exp_f32_e32 v121, v121
	v_pk_add_f32 v[118:119], v[118:119], 1.0 op_sel_hi:[1,0]
	v_rcp_f32_e32 v116, v116
	v_rcp_f32_e32 v117, v117
	v_pk_mul_f32 v[108:109], v[108:109], v[114:115]
	v_pk_add_f32 v[120:121], v[120:121], 1.0 op_sel_hi:[1,0]
	v_rcp_f32_e32 v118, v118
	v_rcp_f32_e32 v119, v119
	v_pk_mul_f32 v[110:111], v[110:111], v[116:117]
	v_pk_mul_f32 v[108:109], v[108:109], v[100:101]
	v_rcp_f32_e32 v120, v120
	v_rcp_f32_e32 v121, v121
	v_pk_mul_f32 v[104:105], v[104:105], v[118:119]
	v_pk_mul_f32 v[110:111], v[110:111], v[102:103]
	v_pk_mul_f32 v[106:107], v[106:107], v[120:121]
	v_pk_mul_f32 v[104:105], v[104:105], v[96:97]
	v_pk_mul_f32 v[106:107], v[106:107], v[98:99]
	v_lshl_add_u64 v[100:101], v[112:113], 0, v[136:137]
	v_cvt_pk_bf16_f32 v96, v108, v109
	v_cvt_pk_bf16_f32 v97, v110, v111
	v_cvt_pk_bf16_f32 v98, v104, v105
	v_cvt_pk_bf16_f32 v99, v106, v107
	global_store_dwordx4 v[100:101], v[96:99], off
	s_nop 0
	s_nop 1
	v_or_b32_e32 v96, 32, v146
	v_ashrrev_i32_e32 v97, 31, v96
	v_lshlrev_b64 v[96:97], 6, v[96:97]
	v_lshl_add_u64 v[96:97], s[18:19], 0, v[96:97]
	v_pk_mul_f32 v[98:99], v[92:93], s[98:99]
	v_pk_mul_f32 v[100:101], v[94:95], s[98:99]
	v_pk_mul_f32 v[102:103], v[88:89], s[98:99]
	v_pk_mul_f32 v[104:105], v[90:91], s[98:99]
	v_exp_f32_e32 v98, v98
	v_exp_f32_e32 v99, v99
	v_exp_f32_e32 v100, v100
	v_exp_f32_e32 v101, v101
	v_pk_add_f32 v[98:99], v[98:99], 1.0 op_sel_hi:[1,0]
	v_exp_f32_e32 v102, v102
	v_exp_f32_e32 v103, v103
	v_pk_add_f32 v[100:101], v[100:101], 1.0 op_sel_hi:[1,0]
	v_rcp_f32_e32 v98, v98
	v_rcp_f32_e32 v99, v99
	v_exp_f32_e32 v104, v104
	v_exp_f32_e32 v105, v105
	v_pk_add_f32 v[102:103], v[102:103], 1.0 op_sel_hi:[1,0]
	v_rcp_f32_e32 v100, v100
	v_rcp_f32_e32 v101, v101
	v_pk_mul_f32 v[92:93], v[92:93], v[98:99]
	v_pk_add_f32 v[104:105], v[104:105], 1.0 op_sel_hi:[1,0]
	v_rcp_f32_e32 v102, v102
	v_rcp_f32_e32 v103, v103
	v_pk_mul_f32 v[94:95], v[94:95], v[100:101]
	v_pk_mul_f32 v[92:93], v[92:93], v[84:85]
	v_rcp_f32_e32 v104, v104
	v_rcp_f32_e32 v105, v105
	v_pk_mul_f32 v[88:89], v[88:89], v[102:103]
	v_pk_mul_f32 v[94:95], v[94:95], v[86:87]
	v_pk_mul_f32 v[90:91], v[90:91], v[104:105]
	v_pk_mul_f32 v[88:89], v[88:89], v[80:81]
	v_pk_mul_f32 v[90:91], v[90:91], v[82:83]
	v_lshl_add_u64 v[84:85], v[96:97], 0, v[136:137]
	v_cvt_pk_bf16_f32 v80, v92, v93
	v_cvt_pk_bf16_f32 v81, v94, v95
	v_cvt_pk_bf16_f32 v82, v88, v89
	v_cvt_pk_bf16_f32 v83, v90, v91
	global_store_dwordx4 v[84:85], v[80:83], off
	s_nop 0
	s_nop 1
	v_or_b32_e32 v80, 48, v146
	v_ashrrev_i32_e32 v81, 31, v80
	v_lshlrev_b64 v[80:81], 6, v[80:81]
	v_lshl_add_u64 v[80:81], s[18:19], 0, v[80:81]
	v_pk_mul_f32 v[82:83], v[76:77], s[98:99]
	v_pk_mul_f32 v[84:85], v[78:79], s[98:99]
	v_pk_mul_f32 v[86:87], v[72:73], s[98:99]
	v_pk_mul_f32 v[88:89], v[74:75], s[98:99]
	v_exp_f32_e32 v82, v82
	v_exp_f32_e32 v83, v83
	v_exp_f32_e32 v84, v84
	v_exp_f32_e32 v85, v85
	v_pk_add_f32 v[82:83], v[82:83], 1.0 op_sel_hi:[1,0]
	v_exp_f32_e32 v86, v86
	v_exp_f32_e32 v87, v87
	v_pk_add_f32 v[84:85], v[84:85], 1.0 op_sel_hi:[1,0]
	v_rcp_f32_e32 v82, v82
	v_rcp_f32_e32 v83, v83
	v_exp_f32_e32 v88, v88
	v_exp_f32_e32 v89, v89
	v_pk_add_f32 v[86:87], v[86:87], 1.0 op_sel_hi:[1,0]
	v_rcp_f32_e32 v84, v84
	v_rcp_f32_e32 v85, v85
	v_pk_mul_f32 v[76:77], v[76:77], v[82:83]
	v_pk_add_f32 v[88:89], v[88:89], 1.0 op_sel_hi:[1,0]
	v_rcp_f32_e32 v86, v86
	v_rcp_f32_e32 v87, v87
	v_pk_mul_f32 v[78:79], v[78:79], v[84:85]
	v_pk_mul_f32 v[76:77], v[76:77], v[68:69]
	v_rcp_f32_e32 v88, v88
	v_rcp_f32_e32 v89, v89
	v_pk_mul_f32 v[72:73], v[72:73], v[86:87]
	v_pk_mul_f32 v[78:79], v[78:79], v[70:71]
	v_pk_mul_f32 v[74:75], v[74:75], v[88:89]
	v_pk_mul_f32 v[72:73], v[72:73], v[64:65]
	v_pk_mul_f32 v[74:75], v[74:75], v[66:67]
	v_lshl_add_u64 v[68:69], v[80:81], 0, v[136:137]
	v_cvt_pk_bf16_f32 v64, v76, v77
	v_cvt_pk_bf16_f32 v65, v78, v79
	v_cvt_pk_bf16_f32 v66, v72, v73
	v_cvt_pk_bf16_f32 v67, v74, v75
	global_store_dwordx4 v[68:69], v[64:67], off
	s_nop 0
	s_nop 1
	v_add_u32_e32 v64, 0x80, v146
	v_ashrrev_i32_e32 v65, 31, v64
	v_lshlrev_b64 v[64:65], 6, v[64:65]
	v_lshl_add_u64 v[64:65], s[18:19], 0, v[64:65]
	v_pk_mul_f32 v[66:67], v[60:61], s[98:99]
	v_pk_mul_f32 v[68:69], v[62:63], s[98:99]
	v_pk_mul_f32 v[70:71], v[56:57], s[98:99]
	v_pk_mul_f32 v[72:73], v[58:59], s[98:99]
	v_exp_f32_e32 v66, v66
	v_exp_f32_e32 v67, v67
	v_exp_f32_e32 v68, v68
	v_exp_f32_e32 v69, v69
	v_pk_add_f32 v[66:67], v[66:67], 1.0 op_sel_hi:[1,0]
	v_exp_f32_e32 v70, v70
	v_exp_f32_e32 v71, v71
	v_pk_add_f32 v[68:69], v[68:69], 1.0 op_sel_hi:[1,0]
	v_rcp_f32_e32 v66, v66
	v_rcp_f32_e32 v67, v67
	v_exp_f32_e32 v72, v72
	v_exp_f32_e32 v73, v73
	v_pk_add_f32 v[70:71], v[70:71], 1.0 op_sel_hi:[1,0]
	v_rcp_f32_e32 v68, v68
	v_rcp_f32_e32 v69, v69
	v_pk_mul_f32 v[60:61], v[60:61], v[66:67]
	v_pk_add_f32 v[72:73], v[72:73], 1.0 op_sel_hi:[1,0]
	v_rcp_f32_e32 v70, v70
	v_rcp_f32_e32 v71, v71
	v_pk_mul_f32 v[62:63], v[62:63], v[68:69]
	v_pk_mul_f32 v[60:61], v[60:61], v[52:53]
	v_rcp_f32_e32 v72, v72
	v_rcp_f32_e32 v73, v73
	v_pk_mul_f32 v[56:57], v[56:57], v[70:71]
	v_pk_mul_f32 v[62:63], v[62:63], v[54:55]
	v_pk_mul_f32 v[58:59], v[58:59], v[72:73]
	v_pk_mul_f32 v[56:57], v[56:57], v[48:49]
	v_pk_mul_f32 v[58:59], v[58:59], v[50:51]
	v_lshl_add_u64 v[52:53], v[64:65], 0, v[136:137]
	v_cvt_pk_bf16_f32 v48, v60, v61
	v_cvt_pk_bf16_f32 v49, v62, v63
	v_cvt_pk_bf16_f32 v50, v56, v57
	v_cvt_pk_bf16_f32 v51, v58, v59
	global_store_dwordx4 v[52:53], v[48:51], off
	s_nop 0
	s_nop 1
	v_add_u32_e32 v48, 0x90, v146
	v_ashrrev_i32_e32 v49, 31, v48
	v_lshlrev_b64 v[48:49], 6, v[48:49]
	v_lshl_add_u64 v[48:49], s[18:19], 0, v[48:49]
	v_pk_mul_f32 v[50:51], v[44:45], s[98:99]
	v_pk_mul_f32 v[52:53], v[46:47], s[98:99]
	v_pk_mul_f32 v[54:55], v[40:41], s[98:99]
	v_pk_mul_f32 v[56:57], v[42:43], s[98:99]
	v_exp_f32_e32 v50, v50
	v_exp_f32_e32 v51, v51
	v_exp_f32_e32 v52, v52
	v_exp_f32_e32 v53, v53
	v_pk_add_f32 v[50:51], v[50:51], 1.0 op_sel_hi:[1,0]
	v_exp_f32_e32 v54, v54
	v_exp_f32_e32 v55, v55
	v_pk_add_f32 v[52:53], v[52:53], 1.0 op_sel_hi:[1,0]
	v_rcp_f32_e32 v50, v50
	v_rcp_f32_e32 v51, v51
	v_exp_f32_e32 v56, v56
	v_exp_f32_e32 v57, v57
	v_pk_add_f32 v[54:55], v[54:55], 1.0 op_sel_hi:[1,0]
	v_rcp_f32_e32 v52, v52
	v_rcp_f32_e32 v53, v53
	v_pk_mul_f32 v[44:45], v[44:45], v[50:51]
	v_pk_add_f32 v[56:57], v[56:57], 1.0 op_sel_hi:[1,0]
	v_rcp_f32_e32 v54, v54
	v_rcp_f32_e32 v55, v55
	v_pk_mul_f32 v[46:47], v[46:47], v[52:53]
	v_pk_mul_f32 v[44:45], v[44:45], v[36:37]
	v_rcp_f32_e32 v56, v56
	v_rcp_f32_e32 v57, v57
	v_pk_mul_f32 v[40:41], v[40:41], v[54:55]
	v_pk_mul_f32 v[46:47], v[46:47], v[38:39]
	v_pk_mul_f32 v[42:43], v[42:43], v[56:57]
	v_pk_mul_f32 v[40:41], v[40:41], v[32:33]
	v_pk_mul_f32 v[42:43], v[42:43], v[34:35]
	v_lshl_add_u64 v[36:37], v[48:49], 0, v[136:137]
	v_cvt_pk_bf16_f32 v32, v44, v45
	v_cvt_pk_bf16_f32 v33, v46, v47
	v_cvt_pk_bf16_f32 v34, v40, v41
	v_cvt_pk_bf16_f32 v35, v42, v43
	global_store_dwordx4 v[36:37], v[32:35], off
	s_nop 0
	s_nop 1
	v_add_u32_e32 v32, 0xa0, v146
	v_ashrrev_i32_e32 v33, 31, v32
	v_lshlrev_b64 v[32:33], 6, v[32:33]
	v_lshl_add_u64 v[32:33], s[18:19], 0, v[32:33]
	v_pk_mul_f32 v[34:35], v[28:29], s[98:99]
	v_pk_mul_f32 v[36:37], v[30:31], s[98:99]
	v_pk_mul_f32 v[38:39], v[24:25], s[98:99]
	v_pk_mul_f32 v[40:41], v[26:27], s[98:99]
	v_exp_f32_e32 v34, v34
	v_exp_f32_e32 v35, v35
	v_exp_f32_e32 v36, v36
	v_exp_f32_e32 v37, v37
	v_pk_add_f32 v[34:35], v[34:35], 1.0 op_sel_hi:[1,0]
	v_exp_f32_e32 v38, v38
	v_exp_f32_e32 v39, v39
	v_pk_add_f32 v[36:37], v[36:37], 1.0 op_sel_hi:[1,0]
	v_rcp_f32_e32 v34, v34
	v_rcp_f32_e32 v35, v35
	v_exp_f32_e32 v40, v40
	v_exp_f32_e32 v41, v41
	v_pk_add_f32 v[38:39], v[38:39], 1.0 op_sel_hi:[1,0]
	v_rcp_f32_e32 v36, v36
	v_rcp_f32_e32 v37, v37
	v_pk_mul_f32 v[28:29], v[28:29], v[34:35]
	v_pk_add_f32 v[40:41], v[40:41], 1.0 op_sel_hi:[1,0]
	v_rcp_f32_e32 v38, v38
	v_rcp_f32_e32 v39, v39
	v_pk_mul_f32 v[30:31], v[30:31], v[36:37]
	v_pk_mul_f32 v[28:29], v[28:29], v[20:21]
	v_rcp_f32_e32 v40, v40
	v_rcp_f32_e32 v41, v41
	v_pk_mul_f32 v[24:25], v[24:25], v[38:39]
	v_pk_mul_f32 v[30:31], v[30:31], v[22:23]
	v_pk_mul_f32 v[26:27], v[26:27], v[40:41]
	v_pk_mul_f32 v[24:25], v[24:25], v[16:17]
	v_pk_mul_f32 v[26:27], v[26:27], v[18:19]
	v_lshl_add_u64 v[20:21], v[32:33], 0, v[136:137]
	v_cvt_pk_bf16_f32 v16, v28, v29
	v_cvt_pk_bf16_f32 v17, v30, v31
	v_cvt_pk_bf16_f32 v18, v24, v25
	v_cvt_pk_bf16_f32 v19, v26, v27
	global_store_dwordx4 v[20:21], v[16:19], off
	s_nop 0
	s_nop 1
	v_add_u32_e32 v16, 0xb0, v146
	v_ashrrev_i32_e32 v17, 31, v16
	v_lshlrev_b64 v[16:17], 6, v[16:17]
	v_lshl_add_u64 v[16:17], s[18:19], 0, v[16:17]
	v_pk_mul_f32 v[18:19], v[12:13], s[98:99]
	v_pk_mul_f32 v[20:21], v[14:15], s[98:99]
	v_pk_mul_f32 v[22:23], v[8:9], s[98:99]
	v_pk_mul_f32 v[24:25], v[10:11], s[98:99]
	v_exp_f32_e32 v18, v18
	v_exp_f32_e32 v19, v19
	v_exp_f32_e32 v20, v20
	v_exp_f32_e32 v21, v21
	v_pk_add_f32 v[18:19], v[18:19], 1.0 op_sel_hi:[1,0]
	v_exp_f32_e32 v22, v22
	v_exp_f32_e32 v23, v23
	v_pk_add_f32 v[20:21], v[20:21], 1.0 op_sel_hi:[1,0]
	v_rcp_f32_e32 v18, v18
	v_rcp_f32_e32 v19, v19
	v_exp_f32_e32 v24, v24
	v_exp_f32_e32 v25, v25
	v_pk_add_f32 v[22:23], v[22:23], 1.0 op_sel_hi:[1,0]
	v_rcp_f32_e32 v20, v20
	v_rcp_f32_e32 v21, v21
	v_pk_mul_f32 v[12:13], v[12:13], v[18:19]
	v_pk_add_f32 v[24:25], v[24:25], 1.0 op_sel_hi:[1,0]
	v_rcp_f32_e32 v22, v22
	v_rcp_f32_e32 v23, v23
	v_pk_mul_f32 v[14:15], v[14:15], v[20:21]
	v_pk_mul_f32 v[12:13], v[12:13], v[4:5]
	v_rcp_f32_e32 v24, v24
	v_rcp_f32_e32 v25, v25
	v_pk_mul_f32 v[8:9], v[8:9], v[22:23]
	v_pk_mul_f32 v[14:15], v[14:15], v[6:7]
	v_pk_mul_f32 v[10:11], v[10:11], v[24:25]
	v_pk_mul_f32 v[8:9], v[8:9], v[0:1]
	v_pk_mul_f32 v[10:11], v[10:11], v[2:3]
	v_lshl_add_u64 v[4:5], v[16:17], 0, v[136:137]
	v_cvt_pk_bf16_f32 v0, v12, v13
	v_cvt_pk_bf16_f32 v1, v14, v15
	v_cvt_pk_bf16_f32 v2, v8, v9
	v_cvt_pk_bf16_f32 v3, v10, v11
	global_store_dwordx4 v[4:5], v[0:3], off
	s_cbranch_vccnz .LBB0_952
	s_andn2_b64 vcc, exec, s[4:5]
	s_cbranch_vccnz .LBB0_951
	s_barrier
	s_branch .LBB0_951
